# C + s_setprio flips removed from the four SP2 loops
# speedup vs baseline: 1.0044x; 1.0044x over previous
.Lsk1_p1:
	s_waitcnt lgkmcnt(0)
	s_barrier
	v_mfma_f32_16x16x32_bf16 v[126:129], v[130:133], v[162:165], v[126:129]
	v_mfma_f32_16x16x32_bf16 v[122:125], v[148:151], v[162:165], v[122:125]
	v_mfma_f32_16x16x32_bf16 v[118:121], v[130:133], v[170:173], v[118:121]
	v_mfma_f32_16x16x32_bf16 v[114:117], v[148:151], v[170:173], v[114:117]
	v_mfma_f32_16x16x32_bf16 v[110:113], v[130:133], v[178:181], v[110:113]
	v_mfma_f32_16x16x32_bf16 v[106:109], v[148:151], v[178:181], v[106:109]
	v_mfma_f32_16x16x32_bf16 v[102:105], v[130:133], v[186:189], v[102:105]
	v_mfma_f32_16x16x32_bf16 v[98:101], v[148:151], v[186:189], v[98:101]
	v_mfma_f32_16x16x32_bf16 v[126:129], v[134:137], v[166:169], v[126:129]
	v_mfma_f32_16x16x32_bf16 v[122:125], v[158:161], v[166:169], v[122:125]
	v_mfma_f32_16x16x32_bf16 v[118:121], v[134:137], v[174:177], v[118:121]
	v_mfma_f32_16x16x32_bf16 v[114:117], v[158:161], v[174:177], v[114:117]
	v_mfma_f32_16x16x32_bf16 v[110:113], v[134:137], v[182:185], v[110:113]
	v_mfma_f32_16x16x32_bf16 v[106:109], v[158:161], v[182:185], v[106:109]
	v_mfma_f32_16x16x32_bf16 v[102:105], v[134:137], v[190:193], v[102:105]
	v_mfma_f32_16x16x32_bf16 v[98:101], v[158:161], v[190:193], v[98:101]
	v_mfma_f32_16x16x32_bf16 v[62:65], v[194:197], v[162:165], v[62:65]
	v_mfma_f32_16x16x32_bf16 v[58:61], v[202:205], v[162:165], v[58:61]
	v_mfma_f32_16x16x32_bf16 v[54:57], v[194:197], v[170:173], v[54:57]
	v_mfma_f32_16x16x32_bf16 v[50:53], v[202:205], v[170:173], v[50:53]
	v_mfma_f32_16x16x32_bf16 v[46:49], v[194:197], v[178:181], v[46:49]
	v_mfma_f32_16x16x32_bf16 v[42:45], v[202:205], v[178:181], v[42:45]
	v_mfma_f32_16x16x32_bf16 v[38:41], v[194:197], v[186:189], v[38:41]
	v_mfma_f32_16x16x32_bf16 v[34:37], v[202:205], v[186:189], v[34:37]
	v_mfma_f32_16x16x32_bf16 v[62:65], v[198:201], v[166:169], v[62:65]
	v_mfma_f32_16x16x32_bf16 v[58:61], v[206:209], v[166:169], v[58:61]
	v_mfma_f32_16x16x32_bf16 v[54:57], v[198:201], v[174:177], v[54:57]
	v_mfma_f32_16x16x32_bf16 v[50:53], v[206:209], v[174:177], v[50:53]
	v_mfma_f32_16x16x32_bf16 v[46:49], v[198:201], v[182:185], v[46:49]
	v_mfma_f32_16x16x32_bf16 v[42:45], v[206:209], v[182:185], v[42:45]
	v_mfma_f32_16x16x32_bf16 v[38:41], v[198:201], v[190:193], v[38:41]
	v_mfma_f32_16x16x32_bf16 v[34:37], v[206:209], v[190:193], v[34:37]
	s_barrier
	ds_read_b128 v[162:165], v156 offset:16384
	ds_read_b128 v[166:169], v156 offset:17408
	ds_read_b128 v[170:173], v156 offset:18432
	ds_read_b128 v[174:177], v156 offset:19456
	ds_read_b128 v[178:181], v156 offset:20480
	ds_read_b128 v[182:185], v156 offset:21504
	ds_read_b128 v[186:189], v156 offset:22528
	ds_read_b128 v[190:193], v156 offset:23552
	v_lshl_add_u64 v[212:213], s[0:1], 0, v[140:141]
	v_lshl_add_u64 v[210:211], s[30:31], 0, v[138:139]
	s_add_i32 s30, s75, s5
	s_mov_b32 m0, s30
	s_nop 0
	global_load_lds_dwordx4 v[210:211], off
	v_lshl_add_u64 v[214:215], v[210:211], 0, s[14:15]
	s_add_i32 m0, s30, 0x2000
	s_nop 0
	global_load_lds_dwordx4 v[214:215], off
	s_add_i32 s0, s76, s5
	v_lshl_add_u64 v[250:251], v[210:211], 0, s[16:17]
	s_mov_b32 m0, s0
	s_nop 0
	global_load_lds_dwordx4 v[250:251], off
	v_lshl_add_u64 v[250:251], v[210:211], 0, s[18:19]
	s_add_i32 m0, s0, 0x2000
	s_nop 0
	global_load_lds_dwordx4 v[250:251], off
	s_mov_b32 m0, s7
	s_nop 0
	global_load_lds_dwordx4 v[212:213], off
	v_lshl_add_u64 v[214:215], v[212:213], 0, s[14:15]
	s_mov_b32 m0, s24
	s_nop 0
	global_load_lds_dwordx4 v[214:215], off
	s_cmp_lg_u32 s98, 0
	s_cbranch_scc1 .Lsk2_p1
	s_waitcnt vmcnt(8)
	s_branch .Lsk3_p1

.Lsk3_p1:
	s_waitcnt lgkmcnt(0)
	s_barrier
	v_mfma_f32_16x16x32_bf16 v[94:97], v[130:133], v[162:165], v[94:97]
	v_mfma_f32_16x16x32_bf16 v[90:93], v[148:151], v[162:165], v[90:93]
	v_mfma_f32_16x16x32_bf16 v[86:89], v[130:133], v[170:173], v[86:89]
	v_mfma_f32_16x16x32_bf16 v[82:85], v[148:151], v[170:173], v[82:85]
	v_mfma_f32_16x16x32_bf16 v[78:81], v[130:133], v[178:181], v[78:81]
	v_mfma_f32_16x16x32_bf16 v[74:77], v[148:151], v[178:181], v[74:77]
	v_mfma_f32_16x16x32_bf16 v[70:73], v[130:133], v[186:189], v[70:73]
	v_mfma_f32_16x16x32_bf16 v[66:69], v[148:151], v[186:189], v[66:69]
	v_mfma_f32_16x16x32_bf16 v[94:97], v[134:137], v[166:169], v[94:97]
	v_mfma_f32_16x16x32_bf16 v[90:93], v[158:161], v[166:169], v[90:93]
	v_mfma_f32_16x16x32_bf16 v[86:89], v[134:137], v[174:177], v[86:89]
	v_mfma_f32_16x16x32_bf16 v[82:85], v[158:161], v[174:177], v[82:85]
	v_mfma_f32_16x16x32_bf16 v[78:81], v[134:137], v[182:185], v[78:81]
	v_mfma_f32_16x16x32_bf16 v[74:77], v[158:161], v[182:185], v[74:77]
	v_mfma_f32_16x16x32_bf16 v[70:73], v[134:137], v[190:193], v[70:73]
	v_mfma_f32_16x16x32_bf16 v[66:69], v[158:161], v[190:193], v[66:69]
	v_mfma_f32_16x16x32_bf16 v[30:33], v[194:197], v[162:165], v[30:33]
	v_mfma_f32_16x16x32_bf16 v[26:29], v[202:205], v[162:165], v[26:29]
	v_mfma_f32_16x16x32_bf16 v[22:25], v[194:197], v[170:173], v[22:25]
	v_mfma_f32_16x16x32_bf16 v[18:21], v[202:205], v[170:173], v[18:21]
	v_mfma_f32_16x16x32_bf16 v[14:17], v[194:197], v[178:181], v[14:17]
	v_mfma_f32_16x16x32_bf16 v[10:13], v[202:205], v[178:181], v[10:13]
	v_mfma_f32_16x16x32_bf16 v[6:9], v[194:197], v[186:189], v[6:9]
	v_mfma_f32_16x16x32_bf16 v[2:5], v[202:205], v[186:189], v[2:5]
	v_mfma_f32_16x16x32_bf16 v[30:33], v[198:201], v[166:169], v[30:33]
	v_mfma_f32_16x16x32_bf16 v[26:29], v[206:209], v[166:169], v[26:29]
	v_mfma_f32_16x16x32_bf16 v[22:25], v[198:201], v[174:177], v[22:25]
	v_mfma_f32_16x16x32_bf16 v[18:21], v[206:209], v[174:177], v[18:21]
	v_mfma_f32_16x16x32_bf16 v[14:17], v[198:201], v[182:185], v[14:17]
	v_mfma_f32_16x16x32_bf16 v[10:13], v[206:209], v[182:185], v[10:13]
	v_mfma_f32_16x16x32_bf16 v[6:9], v[198:201], v[190:193], v[6:9]
	v_mfma_f32_16x16x32_bf16 v[2:5], v[206:209], v[190:193], v[2:5]
	s_add_i32 s0, 0, 0x18000
	v_add_u32_e32 v158, s0, v154
	s_barrier
	s_add_i32 s1, 0, 0x1c000
	v_add_u32_e32 v206, s1, v154
	ds_read_b128 v[130:133], v158
	ds_read_b128 v[134:137], v158 offset:1024
	ds_read_b128 v[148:151], v158 offset:2048
	ds_read_b128 v[158:161], v158 offset:3072
	ds_read_b128 v[194:197], v206
	ds_read_b128 v[198:201], v206 offset:1024
	ds_read_b128 v[202:205], v206 offset:2048
	ds_read_b128 v[206:209], v206 offset:3072
	s_mov_b32 m0, s25
	v_lshl_add_u64 v[252:253], v[212:213], 0, s[16:17]
	ds_read_b128 v[162:165], v156 offset:32768
	ds_read_b128 v[166:169], v156 offset:33792
	ds_read_b128 v[170:173], v156 offset:34816
	ds_read_b128 v[174:177], v156 offset:35840
	ds_read_b128 v[178:181], v156 offset:36864
	ds_read_b128 v[182:185], v156 offset:37888
	ds_read_b128 v[186:189], v156 offset:38912
	ds_read_b128 v[190:193], v156 offset:39936
	global_load_lds_dwordx4 v[252:253], off
	v_lshl_add_u64 v[252:253], v[212:213], 0, s[18:19]
	s_mov_b32 m0, s26
	s_nop 0
	global_load_lds_dwordx4 v[252:253], off
	s_waitcnt vmcnt(8)
	s_waitcnt lgkmcnt(0)
	s_barrier
	v_mfma_f32_16x16x32_bf16 v[126:129], v[130:133], v[162:165], v[126:129]
	v_mfma_f32_16x16x32_bf16 v[122:125], v[148:151], v[162:165], v[122:125]
	v_mfma_f32_16x16x32_bf16 v[118:121], v[130:133], v[170:173], v[118:121]
	v_mfma_f32_16x16x32_bf16 v[114:117], v[148:151], v[170:173], v[114:117]
	v_mfma_f32_16x16x32_bf16 v[110:113], v[130:133], v[178:181], v[110:113]
	v_mfma_f32_16x16x32_bf16 v[106:109], v[148:151], v[178:181], v[106:109]
	v_mfma_f32_16x16x32_bf16 v[102:105], v[130:133], v[186:189], v[102:105]
	v_mfma_f32_16x16x32_bf16 v[98:101], v[148:151], v[186:189], v[98:101]
	v_mfma_f32_16x16x32_bf16 v[126:129], v[134:137], v[166:169], v[126:129]
	v_mfma_f32_16x16x32_bf16 v[122:125], v[158:161], v[166:169], v[122:125]
	v_mfma_f32_16x16x32_bf16 v[118:121], v[134:137], v[174:177], v[118:121]
	v_mfma_f32_16x16x32_bf16 v[114:117], v[158:161], v[174:177], v[114:117]
	v_mfma_f32_16x16x32_bf16 v[110:113], v[134:137], v[182:185], v[110:113]
	v_mfma_f32_16x16x32_bf16 v[106:109], v[158:161], v[182:185], v[106:109]
	v_mfma_f32_16x16x32_bf16 v[102:105], v[134:137], v[190:193], v[102:105]
	v_mfma_f32_16x16x32_bf16 v[98:101], v[158:161], v[190:193], v[98:101]
	v_mfma_f32_16x16x32_bf16 v[62:65], v[194:197], v[162:165], v[62:65]
	v_mfma_f32_16x16x32_bf16 v[58:61], v[202:205], v[162:165], v[58:61]
	v_mfma_f32_16x16x32_bf16 v[54:57], v[194:197], v[170:173], v[54:57]
	v_mfma_f32_16x16x32_bf16 v[50:53], v[202:205], v[170:173], v[50:53]
	v_mfma_f32_16x16x32_bf16 v[46:49], v[194:197], v[178:181], v[46:49]
	v_mfma_f32_16x16x32_bf16 v[42:45], v[202:205], v[178:181], v[42:45]
	v_mfma_f32_16x16x32_bf16 v[38:41], v[194:197], v[186:189], v[38:41]
	v_mfma_f32_16x16x32_bf16 v[34:37], v[202:205], v[186:189], v[34:37]
	v_mfma_f32_16x16x32_bf16 v[62:65], v[198:201], v[166:169], v[62:65]
	v_mfma_f32_16x16x32_bf16 v[58:61], v[206:209], v[166:169], v[58:61]
	v_mfma_f32_16x16x32_bf16 v[54:57], v[198:201], v[174:177], v[54:57]
	v_mfma_f32_16x16x32_bf16 v[50:53], v[206:209], v[174:177], v[50:53]
	v_mfma_f32_16x16x32_bf16 v[46:49], v[198:201], v[182:185], v[46:49]
	v_mfma_f32_16x16x32_bf16 v[42:45], v[206:209], v[182:185], v[42:45]
	v_mfma_f32_16x16x32_bf16 v[38:41], v[198:201], v[190:193], v[38:41]
	v_mfma_f32_16x16x32_bf16 v[34:37], v[206:209], v[190:193], v[34:37]
	s_barrier
	ds_read_b128 v[162:165], v156 offset:49152
	ds_read_b128 v[166:169], v156 offset:50176
	ds_read_b128 v[170:173], v156 offset:51200
	ds_read_b128 v[174:177], v156 offset:52224
	ds_read_b128 v[178:181], v156 offset:53248
	ds_read_b128 v[182:185], v156 offset:54272
	ds_read_b128 v[186:189], v156 offset:55296
	ds_read_b128 v[190:193], v156 offset:56320
	s_add_i32 s0, s0, s5
	v_lshl_add_u64 v[214:215], v[210:211], 0, s[38:39]
	s_mov_b32 m0, s0
	s_nop 0
	global_load_lds_dwordx4 v[214:215], off
	v_lshl_add_u64 v[214:215], v[210:211], 0, s[42:43]
	s_add_i32 m0, s0, 0x2000
	s_nop 0
	global_load_lds_dwordx4 v[214:215], off
	s_add_i32 s0, s1, s5
	v_lshl_add_u64 v[250:251], v[210:211], 0, s[44:45]
	s_mov_b32 m0, s0
	s_nop 0
	global_load_lds_dwordx4 v[250:251], off
	v_lshl_add_u64 v[250:251], v[210:211], 0, s[46:47]
	s_add_i32 m0, s0, 0x2000
	s_nop 0
	global_load_lds_dwordx4 v[250:251], off
	s_mov_b32 m0, s37
	v_lshl_add_u64 v[214:215], v[212:213], 0, s[38:39]
	global_load_lds_dwordx4 v[214:215], off
	v_lshl_add_u64 v[212:213], v[212:213], 0, s[42:43]
	s_mov_b32 m0, s40
	s_nop 0
	global_load_lds_dwordx4 v[212:213], off
	s_waitcnt vmcnt(8)
	s_waitcnt lgkmcnt(0)
	s_barrier
	v_mfma_f32_16x16x32_bf16 v[94:97], v[130:133], v[162:165], v[94:97]
	v_mfma_f32_16x16x32_bf16 v[90:93], v[148:151], v[162:165], v[90:93]
	v_mfma_f32_16x16x32_bf16 v[86:89], v[130:133], v[170:173], v[86:89]
	v_mfma_f32_16x16x32_bf16 v[82:85], v[148:151], v[170:173], v[82:85]
	v_mfma_f32_16x16x32_bf16 v[78:81], v[130:133], v[178:181], v[78:81]
	v_mfma_f32_16x16x32_bf16 v[74:77], v[148:151], v[178:181], v[74:77]
	v_mfma_f32_16x16x32_bf16 v[70:73], v[130:133], v[186:189], v[70:73]
	v_mfma_f32_16x16x32_bf16 v[66:69], v[148:151], v[186:189], v[66:69]
	v_mfma_f32_16x16x32_bf16 v[94:97], v[134:137], v[166:169], v[94:97]
	v_mfma_f32_16x16x32_bf16 v[90:93], v[158:161], v[166:169], v[90:93]
	v_mfma_f32_16x16x32_bf16 v[86:89], v[134:137], v[174:177], v[86:89]
	v_mfma_f32_16x16x32_bf16 v[82:85], v[158:161], v[174:177], v[82:85]
	v_mfma_f32_16x16x32_bf16 v[78:81], v[134:137], v[182:185], v[78:81]
	v_mfma_f32_16x16x32_bf16 v[74:77], v[158:161], v[182:185], v[74:77]
	v_mfma_f32_16x16x32_bf16 v[70:73], v[134:137], v[190:193], v[70:73]
	v_mfma_f32_16x16x32_bf16 v[66:69], v[158:161], v[190:193], v[66:69]
	v_mfma_f32_16x16x32_bf16 v[30:33], v[194:197], v[162:165], v[30:33]
	v_mfma_f32_16x16x32_bf16 v[26:29], v[202:205], v[162:165], v[26:29]
	v_mfma_f32_16x16x32_bf16 v[22:25], v[194:197], v[170:173], v[22:25]
	v_mfma_f32_16x16x32_bf16 v[18:21], v[202:205], v[170:173], v[18:21]
	v_mfma_f32_16x16x32_bf16 v[14:17], v[194:197], v[178:181], v[14:17]
	v_mfma_f32_16x16x32_bf16 v[10:13], v[202:205], v[178:181], v[10:13]
	v_mfma_f32_16x16x32_bf16 v[6:9], v[194:197], v[186:189], v[6:9]
	v_mfma_f32_16x16x32_bf16 v[2:5], v[202:205], v[186:189], v[2:5]
	v_mfma_f32_16x16x32_bf16 v[30:33], v[198:201], v[166:169], v[30:33]
	v_mfma_f32_16x16x32_bf16 v[26:29], v[206:209], v[166:169], v[26:29]
	v_mfma_f32_16x16x32_bf16 v[22:25], v[198:201], v[174:177], v[22:25]
	v_mfma_f32_16x16x32_bf16 v[18:21], v[206:209], v[174:177], v[18:21]
	v_mfma_f32_16x16x32_bf16 v[14:17], v[198:201], v[182:185], v[14:17]
	v_mfma_f32_16x16x32_bf16 v[10:13], v[206:209], v[182:185], v[10:13]
	v_mfma_f32_16x16x32_bf16 v[6:9], v[198:201], v[190:193], v[6:9]
	v_mfma_f32_16x16x32_bf16 v[2:5], v[206:209], v[190:193], v[2:5]
	s_add_i32 s68, s68, 2
	s_add_u32 s66, s66, 0x100
	s_addc_u32 s67, s67, 0
	s_add_u32 s64, s64, 0x100
	s_addc_u32 s65, s65, 0
	s_cmp_gt_u32 s68, 13
	s_barrier
	s_cbranch_scc0 .LBB0_190
	s_mov_b32 s98, 1
	s_and_b64 vcc, exec, s[48:49]
	s_cbranch_vccz .LBB0_193
	s_barrier

.Lsk1_p7:
	s_waitcnt lgkmcnt(0)
	s_barrier
	v_mfma_f32_16x16x32_bf16 v[126:129], v[130:133], v[162:165], v[126:129]
	v_mfma_f32_16x16x32_bf16 v[122:125], v[148:151], v[162:165], v[122:125]
	v_mfma_f32_16x16x32_bf16 v[118:121], v[130:133], v[170:173], v[118:121]
	v_mfma_f32_16x16x32_bf16 v[114:117], v[148:151], v[170:173], v[114:117]
	v_mfma_f32_16x16x32_bf16 v[110:113], v[130:133], v[178:181], v[110:113]
	v_mfma_f32_16x16x32_bf16 v[106:109], v[148:151], v[178:181], v[106:109]
	v_mfma_f32_16x16x32_bf16 v[102:105], v[130:133], v[186:189], v[102:105]
	v_mfma_f32_16x16x32_bf16 v[98:101], v[148:151], v[186:189], v[98:101]
	v_mfma_f32_16x16x32_bf16 v[126:129], v[134:137], v[166:169], v[126:129]
	v_mfma_f32_16x16x32_bf16 v[122:125], v[158:161], v[166:169], v[122:125]
	v_mfma_f32_16x16x32_bf16 v[118:121], v[134:137], v[174:177], v[118:121]
	v_mfma_f32_16x16x32_bf16 v[114:117], v[158:161], v[174:177], v[114:117]
	v_mfma_f32_16x16x32_bf16 v[110:113], v[134:137], v[182:185], v[110:113]
	v_mfma_f32_16x16x32_bf16 v[106:109], v[158:161], v[182:185], v[106:109]
	v_mfma_f32_16x16x32_bf16 v[102:105], v[134:137], v[190:193], v[102:105]
	v_mfma_f32_16x16x32_bf16 v[98:101], v[158:161], v[190:193], v[98:101]
	v_mfma_f32_16x16x32_bf16 v[62:65], v[194:197], v[162:165], v[62:65]
	v_mfma_f32_16x16x32_bf16 v[58:61], v[202:205], v[162:165], v[58:61]
	v_mfma_f32_16x16x32_bf16 v[54:57], v[194:197], v[170:173], v[54:57]
	v_mfma_f32_16x16x32_bf16 v[50:53], v[202:205], v[170:173], v[50:53]
	v_mfma_f32_16x16x32_bf16 v[46:49], v[194:197], v[178:181], v[46:49]
	v_mfma_f32_16x16x32_bf16 v[42:45], v[202:205], v[178:181], v[42:45]
	v_mfma_f32_16x16x32_bf16 v[38:41], v[194:197], v[186:189], v[38:41]
	v_mfma_f32_16x16x32_bf16 v[34:37], v[202:205], v[186:189], v[34:37]
	v_mfma_f32_16x16x32_bf16 v[62:65], v[198:201], v[166:169], v[62:65]
	v_mfma_f32_16x16x32_bf16 v[58:61], v[206:209], v[166:169], v[58:61]
	v_mfma_f32_16x16x32_bf16 v[54:57], v[198:201], v[174:177], v[54:57]
	v_mfma_f32_16x16x32_bf16 v[50:53], v[206:209], v[174:177], v[50:53]
	v_mfma_f32_16x16x32_bf16 v[46:49], v[198:201], v[182:185], v[46:49]
	v_mfma_f32_16x16x32_bf16 v[42:45], v[206:209], v[182:185], v[42:45]
	v_mfma_f32_16x16x32_bf16 v[38:41], v[198:201], v[190:193], v[38:41]
	v_mfma_f32_16x16x32_bf16 v[34:37], v[206:209], v[190:193], v[34:37]
	s_barrier
	ds_read_b128 v[162:165], v156 offset:16384
	ds_read_b128 v[166:169], v156 offset:17408
	ds_read_b128 v[170:173], v156 offset:18432
	ds_read_b128 v[174:177], v156 offset:19456
	ds_read_b128 v[178:181], v156 offset:20480
	ds_read_b128 v[182:185], v156 offset:21504
	ds_read_b128 v[186:189], v156 offset:22528
	ds_read_b128 v[190:193], v156 offset:23552
	v_lshl_add_u64 v[212:213], s[0:1], 0, v[140:141]
	v_lshl_add_u64 v[210:211], s[30:31], 0, v[138:139]
	s_add_i32 s30, s78, s7
	s_mov_b32 m0, s30
	s_nop 0
	global_load_lds_dwordx4 v[210:211], off
	v_lshl_add_u64 v[214:215], v[210:211], 0, s[14:15]
	s_add_i32 m0, s30, 0x2000
	s_nop 0
	global_load_lds_dwordx4 v[214:215], off
	s_add_i32 s0, s79, s7
	v_lshl_add_u64 v[250:251], v[210:211], 0, s[18:19]
	s_mov_b32 m0, s0
	s_nop 0
	global_load_lds_dwordx4 v[250:251], off
	v_lshl_add_u64 v[250:251], v[210:211], 0, s[20:21]
	s_add_i32 m0, s0, 0x2000
	s_nop 0
	global_load_lds_dwordx4 v[250:251], off
	s_mov_b32 m0, s9
	s_nop 0
	global_load_lds_dwordx4 v[212:213], off
	v_lshl_add_u64 v[214:215], v[212:213], 0, s[14:15]
	s_mov_b32 m0, s24
	s_nop 0
	global_load_lds_dwordx4 v[214:215], off
	s_cmp_lg_u32 s98, 0
	s_cbranch_scc1 .Lsk2_p7
	s_waitcnt vmcnt(8)
	s_branch .Lsk3_p7

.Lsk3_p7:
	s_waitcnt lgkmcnt(0)
	s_barrier
	v_mfma_f32_16x16x32_bf16 v[94:97], v[130:133], v[162:165], v[94:97]
	v_mfma_f32_16x16x32_bf16 v[90:93], v[148:151], v[162:165], v[90:93]
	v_mfma_f32_16x16x32_bf16 v[86:89], v[130:133], v[170:173], v[86:89]
	v_mfma_f32_16x16x32_bf16 v[82:85], v[148:151], v[170:173], v[82:85]
	v_mfma_f32_16x16x32_bf16 v[78:81], v[130:133], v[178:181], v[78:81]
	v_mfma_f32_16x16x32_bf16 v[74:77], v[148:151], v[178:181], v[74:77]
	v_mfma_f32_16x16x32_bf16 v[70:73], v[130:133], v[186:189], v[70:73]
	v_mfma_f32_16x16x32_bf16 v[66:69], v[148:151], v[186:189], v[66:69]
	v_mfma_f32_16x16x32_bf16 v[94:97], v[134:137], v[166:169], v[94:97]
	v_mfma_f32_16x16x32_bf16 v[90:93], v[158:161], v[166:169], v[90:93]
	v_mfma_f32_16x16x32_bf16 v[86:89], v[134:137], v[174:177], v[86:89]
	v_mfma_f32_16x16x32_bf16 v[82:85], v[158:161], v[174:177], v[82:85]
	v_mfma_f32_16x16x32_bf16 v[78:81], v[134:137], v[182:185], v[78:81]
	v_mfma_f32_16x16x32_bf16 v[74:77], v[158:161], v[182:185], v[74:77]
	v_mfma_f32_16x16x32_bf16 v[70:73], v[134:137], v[190:193], v[70:73]
	v_mfma_f32_16x16x32_bf16 v[66:69], v[158:161], v[190:193], v[66:69]
	v_mfma_f32_16x16x32_bf16 v[30:33], v[194:197], v[162:165], v[30:33]
	v_mfma_f32_16x16x32_bf16 v[26:29], v[202:205], v[162:165], v[26:29]
	v_mfma_f32_16x16x32_bf16 v[22:25], v[194:197], v[170:173], v[22:25]
	v_mfma_f32_16x16x32_bf16 v[18:21], v[202:205], v[170:173], v[18:21]
	v_mfma_f32_16x16x32_bf16 v[14:17], v[194:197], v[178:181], v[14:17]
	v_mfma_f32_16x16x32_bf16 v[10:13], v[202:205], v[178:181], v[10:13]
	v_mfma_f32_16x16x32_bf16 v[6:9], v[194:197], v[186:189], v[6:9]
	v_mfma_f32_16x16x32_bf16 v[2:5], v[202:205], v[186:189], v[2:5]
	v_mfma_f32_16x16x32_bf16 v[30:33], v[198:201], v[166:169], v[30:33]
	v_mfma_f32_16x16x32_bf16 v[26:29], v[206:209], v[166:169], v[26:29]
	v_mfma_f32_16x16x32_bf16 v[22:25], v[198:201], v[174:177], v[22:25]
	v_mfma_f32_16x16x32_bf16 v[18:21], v[206:209], v[174:177], v[18:21]
	v_mfma_f32_16x16x32_bf16 v[14:17], v[198:201], v[182:185], v[14:17]
	v_mfma_f32_16x16x32_bf16 v[10:13], v[206:209], v[182:185], v[10:13]
	v_mfma_f32_16x16x32_bf16 v[6:9], v[198:201], v[190:193], v[6:9]
	v_mfma_f32_16x16x32_bf16 v[2:5], v[206:209], v[190:193], v[2:5]
	s_add_i32 s0, 0, 0x18000
	v_add_u32_e32 v158, s0, v154
	s_barrier
	s_add_i32 s1, 0, 0x1c000
	v_add_u32_e32 v206, s1, v154
	ds_read_b128 v[130:133], v158
	ds_read_b128 v[134:137], v158 offset:1024
	ds_read_b128 v[148:151], v158 offset:2048
	ds_read_b128 v[158:161], v158 offset:3072
	ds_read_b128 v[194:197], v206
	ds_read_b128 v[198:201], v206 offset:1024
	ds_read_b128 v[202:205], v206 offset:2048
	ds_read_b128 v[206:209], v206 offset:3072
	s_mov_b32 m0, s25
	v_lshl_add_u64 v[252:253], v[212:213], 0, s[18:19]
	ds_read_b128 v[162:165], v156 offset:32768
	ds_read_b128 v[166:169], v156 offset:33792
	ds_read_b128 v[170:173], v156 offset:34816
	ds_read_b128 v[174:177], v156 offset:35840
	ds_read_b128 v[178:181], v156 offset:36864
	ds_read_b128 v[182:185], v156 offset:37888
	ds_read_b128 v[186:189], v156 offset:38912
	ds_read_b128 v[190:193], v156 offset:39936
	global_load_lds_dwordx4 v[252:253], off
	v_lshl_add_u64 v[252:253], v[212:213], 0, s[20:21]
	s_mov_b32 m0, s26
	s_nop 0
	global_load_lds_dwordx4 v[252:253], off
	s_waitcnt vmcnt(8)
	s_waitcnt lgkmcnt(0)
	s_barrier
	v_mfma_f32_16x16x32_bf16 v[126:129], v[130:133], v[162:165], v[126:129]
	v_mfma_f32_16x16x32_bf16 v[122:125], v[148:151], v[162:165], v[122:125]
	v_mfma_f32_16x16x32_bf16 v[118:121], v[130:133], v[170:173], v[118:121]
	v_mfma_f32_16x16x32_bf16 v[114:117], v[148:151], v[170:173], v[114:117]
	v_mfma_f32_16x16x32_bf16 v[110:113], v[130:133], v[178:181], v[110:113]
	v_mfma_f32_16x16x32_bf16 v[106:109], v[148:151], v[178:181], v[106:109]
	v_mfma_f32_16x16x32_bf16 v[102:105], v[130:133], v[186:189], v[102:105]
	v_mfma_f32_16x16x32_bf16 v[98:101], v[148:151], v[186:189], v[98:101]
	v_mfma_f32_16x16x32_bf16 v[126:129], v[134:137], v[166:169], v[126:129]
	v_mfma_f32_16x16x32_bf16 v[122:125], v[158:161], v[166:169], v[122:125]
	v_mfma_f32_16x16x32_bf16 v[118:121], v[134:137], v[174:177], v[118:121]
	v_mfma_f32_16x16x32_bf16 v[114:117], v[158:161], v[174:177], v[114:117]
	v_mfma_f32_16x16x32_bf16 v[110:113], v[134:137], v[182:185], v[110:113]
	v_mfma_f32_16x16x32_bf16 v[106:109], v[158:161], v[182:185], v[106:109]
	v_mfma_f32_16x16x32_bf16 v[102:105], v[134:137], v[190:193], v[102:105]
	v_mfma_f32_16x16x32_bf16 v[98:101], v[158:161], v[190:193], v[98:101]
	v_mfma_f32_16x16x32_bf16 v[62:65], v[194:197], v[162:165], v[62:65]
	v_mfma_f32_16x16x32_bf16 v[58:61], v[202:205], v[162:165], v[58:61]
	v_mfma_f32_16x16x32_bf16 v[54:57], v[194:197], v[170:173], v[54:57]
	v_mfma_f32_16x16x32_bf16 v[50:53], v[202:205], v[170:173], v[50:53]
	v_mfma_f32_16x16x32_bf16 v[46:49], v[194:197], v[178:181], v[46:49]
	v_mfma_f32_16x16x32_bf16 v[42:45], v[202:205], v[178:181], v[42:45]
	v_mfma_f32_16x16x32_bf16 v[38:41], v[194:197], v[186:189], v[38:41]
	v_mfma_f32_16x16x32_bf16 v[34:37], v[202:205], v[186:189], v[34:37]
	v_mfma_f32_16x16x32_bf16 v[62:65], v[198:201], v[166:169], v[62:65]
	v_mfma_f32_16x16x32_bf16 v[58:61], v[206:209], v[166:169], v[58:61]
	v_mfma_f32_16x16x32_bf16 v[54:57], v[198:201], v[174:177], v[54:57]
	v_mfma_f32_16x16x32_bf16 v[50:53], v[206:209], v[174:177], v[50:53]
	v_mfma_f32_16x16x32_bf16 v[46:49], v[198:201], v[182:185], v[46:49]
	v_mfma_f32_16x16x32_bf16 v[42:45], v[206:209], v[182:185], v[42:45]
	v_mfma_f32_16x16x32_bf16 v[38:41], v[198:201], v[190:193], v[38:41]
	v_mfma_f32_16x16x32_bf16 v[34:37], v[206:209], v[190:193], v[34:37]
	s_barrier
	ds_read_b128 v[162:165], v156 offset:49152
	ds_read_b128 v[166:169], v156 offset:50176
	ds_read_b128 v[170:173], v156 offset:51200
	ds_read_b128 v[174:177], v156 offset:52224
	ds_read_b128 v[178:181], v156 offset:53248
	ds_read_b128 v[182:185], v156 offset:54272
	ds_read_b128 v[186:189], v156 offset:55296
	ds_read_b128 v[190:193], v156 offset:56320
	s_add_i32 s0, s0, s7
	v_lshl_add_u64 v[214:215], v[210:211], 0, s[42:43]
	s_mov_b32 m0, s0
	s_nop 0
	global_load_lds_dwordx4 v[214:215], off
	v_lshl_add_u64 v[214:215], v[210:211], 0, s[44:45]
	s_add_i32 m0, s0, 0x2000
	s_nop 0
	global_load_lds_dwordx4 v[214:215], off
	s_add_i32 s0, s1, s7
	v_lshl_add_u64 v[250:251], v[210:211], 0, s[46:47]
	s_mov_b32 m0, s0
	s_nop 0
	global_load_lds_dwordx4 v[250:251], off
	v_lshl_add_u64 v[250:251], v[210:211], 0, s[48:49]
	s_add_i32 m0, s0, 0x2000
	s_nop 0
	global_load_lds_dwordx4 v[250:251], off
	s_mov_b32 m0, s72
	v_lshl_add_u64 v[214:215], v[212:213], 0, s[42:43]
	global_load_lds_dwordx4 v[214:215], off
	v_lshl_add_u64 v[212:213], v[212:213], 0, s[44:45]
	s_mov_b32 m0, s73
	s_nop 0
	global_load_lds_dwordx4 v[212:213], off
	s_waitcnt vmcnt(8)
	s_waitcnt lgkmcnt(0)
	s_barrier
	v_mfma_f32_16x16x32_bf16 v[94:97], v[130:133], v[162:165], v[94:97]
	v_mfma_f32_16x16x32_bf16 v[90:93], v[148:151], v[162:165], v[90:93]
	v_mfma_f32_16x16x32_bf16 v[86:89], v[130:133], v[170:173], v[86:89]
	v_mfma_f32_16x16x32_bf16 v[82:85], v[148:151], v[170:173], v[82:85]
	v_mfma_f32_16x16x32_bf16 v[78:81], v[130:133], v[178:181], v[78:81]
	v_mfma_f32_16x16x32_bf16 v[74:77], v[148:151], v[178:181], v[74:77]
	v_mfma_f32_16x16x32_bf16 v[70:73], v[130:133], v[186:189], v[70:73]
	v_mfma_f32_16x16x32_bf16 v[66:69], v[148:151], v[186:189], v[66:69]
	v_mfma_f32_16x16x32_bf16 v[94:97], v[134:137], v[166:169], v[94:97]
	v_mfma_f32_16x16x32_bf16 v[90:93], v[158:161], v[166:169], v[90:93]
	v_mfma_f32_16x16x32_bf16 v[86:89], v[134:137], v[174:177], v[86:89]
	v_mfma_f32_16x16x32_bf16 v[82:85], v[158:161], v[174:177], v[82:85]
	v_mfma_f32_16x16x32_bf16 v[78:81], v[134:137], v[182:185], v[78:81]
	v_mfma_f32_16x16x32_bf16 v[74:77], v[158:161], v[182:185], v[74:77]
	v_mfma_f32_16x16x32_bf16 v[70:73], v[134:137], v[190:193], v[70:73]
	v_mfma_f32_16x16x32_bf16 v[66:69], v[158:161], v[190:193], v[66:69]
	v_mfma_f32_16x16x32_bf16 v[30:33], v[194:197], v[162:165], v[30:33]
	v_mfma_f32_16x16x32_bf16 v[26:29], v[202:205], v[162:165], v[26:29]
	v_mfma_f32_16x16x32_bf16 v[22:25], v[194:197], v[170:173], v[22:25]
	v_mfma_f32_16x16x32_bf16 v[18:21], v[202:205], v[170:173], v[18:21]
	v_mfma_f32_16x16x32_bf16 v[14:17], v[194:197], v[178:181], v[14:17]
	v_mfma_f32_16x16x32_bf16 v[10:13], v[202:205], v[178:181], v[10:13]
	v_mfma_f32_16x16x32_bf16 v[6:9], v[194:197], v[186:189], v[6:9]
	v_mfma_f32_16x16x32_bf16 v[2:5], v[202:205], v[186:189], v[2:5]
	v_mfma_f32_16x16x32_bf16 v[30:33], v[198:201], v[166:169], v[30:33]
	v_mfma_f32_16x16x32_bf16 v[26:29], v[206:209], v[166:169], v[26:29]
	v_mfma_f32_16x16x32_bf16 v[22:25], v[198:201], v[174:177], v[22:25]
	v_mfma_f32_16x16x32_bf16 v[18:21], v[206:209], v[174:177], v[18:21]
	v_mfma_f32_16x16x32_bf16 v[14:17], v[198:201], v[182:185], v[14:17]
	v_mfma_f32_16x16x32_bf16 v[10:13], v[206:209], v[182:185], v[10:13]
	v_mfma_f32_16x16x32_bf16 v[6:9], v[198:201], v[190:193], v[6:9]
	v_mfma_f32_16x16x32_bf16 v[2:5], v[206:209], v[190:193], v[2:5]
	s_add_i32 s69, s69, 2
	s_add_u32 s38, s38, 0x100
	s_addc_u32 s68, s68, 0
	s_add_u32 s66, s66, 0x100
	s_addc_u32 s67, s67, 0
	s_cmp_gt_u32 s69, 13
	s_barrier
	s_cbranch_scc0 .LBB0_1049
	s_mov_b32 s98, 1
	s_and_b64 vcc, exec, s[50:51]
	s_cbranch_vccz .LBB0_1052
	s_barrier

.Lsk1_p13:
	s_waitcnt lgkmcnt(0)
	s_barrier
	v_mfma_f32_16x16x32_bf16 v[130:133], v[122:125], v[146:149], v[130:133]
	v_mfma_f32_16x16x32_bf16 v[126:129], v[138:141], v[146:149], v[126:129]
	v_mfma_f32_16x16x32_bf16 v[118:121], v[122:125], v[154:157], v[118:121]
	v_mfma_f32_16x16x32_bf16 v[114:117], v[138:141], v[154:157], v[114:117]
	v_mfma_f32_16x16x32_bf16 v[110:113], v[122:125], v[168:171], v[110:113]
	v_mfma_f32_16x16x32_bf16 v[106:109], v[138:141], v[168:171], v[106:109]
	v_mfma_f32_16x16x32_bf16 v[102:105], v[122:125], v[176:179], v[102:105]
	v_mfma_f32_16x16x32_bf16 v[98:101], v[138:141], v[176:179], v[98:101]
	v_mfma_f32_16x16x32_bf16 v[130:133], v[134:137], v[150:153], v[130:133]
	v_mfma_f32_16x16x32_bf16 v[126:129], v[142:145], v[150:153], v[126:129]
	v_mfma_f32_16x16x32_bf16 v[118:121], v[134:137], v[158:161], v[118:121]
	v_mfma_f32_16x16x32_bf16 v[114:117], v[142:145], v[158:161], v[114:117]
	v_mfma_f32_16x16x32_bf16 v[110:113], v[134:137], v[172:175], v[110:113]
	v_mfma_f32_16x16x32_bf16 v[106:109], v[142:145], v[172:175], v[106:109]
	v_mfma_f32_16x16x32_bf16 v[102:105], v[134:137], v[180:183], v[102:105]
	v_mfma_f32_16x16x32_bf16 v[98:101], v[142:145], v[180:183], v[98:101]
	v_mfma_f32_16x16x32_bf16 v[62:65], v[192:195], v[146:149], v[62:65]
	v_mfma_f32_16x16x32_bf16 v[58:61], v[200:203], v[146:149], v[58:61]
	v_mfma_f32_16x16x32_bf16 v[54:57], v[192:195], v[154:157], v[54:57]
	v_mfma_f32_16x16x32_bf16 v[50:53], v[200:203], v[154:157], v[50:53]
	v_mfma_f32_16x16x32_bf16 v[46:49], v[192:195], v[168:171], v[46:49]
	v_mfma_f32_16x16x32_bf16 v[42:45], v[200:203], v[168:171], v[42:45]
	v_mfma_f32_16x16x32_bf16 v[38:41], v[192:195], v[176:179], v[38:41]
	v_mfma_f32_16x16x32_bf16 v[34:37], v[200:203], v[176:179], v[34:37]
	v_mfma_f32_16x16x32_bf16 v[62:65], v[196:199], v[150:153], v[62:65]
	v_mfma_f32_16x16x32_bf16 v[58:61], v[204:207], v[150:153], v[58:61]
	v_mfma_f32_16x16x32_bf16 v[54:57], v[196:199], v[158:161], v[54:57]
	v_mfma_f32_16x16x32_bf16 v[50:53], v[204:207], v[158:161], v[50:53]
	v_mfma_f32_16x16x32_bf16 v[46:49], v[196:199], v[172:175], v[46:49]
	v_mfma_f32_16x16x32_bf16 v[42:45], v[204:207], v[172:175], v[42:45]
	v_mfma_f32_16x16x32_bf16 v[38:41], v[196:199], v[180:183], v[38:41]
	v_mfma_f32_16x16x32_bf16 v[34:37], v[204:207], v[180:183], v[34:37]
	s_barrier
	ds_read_b128 v[146:149], v190 offset:16384
	ds_read_b128 v[150:153], v190 offset:17408
	ds_read_b128 v[154:157], v190 offset:18432
	ds_read_b128 v[158:161], v190 offset:19456
	ds_read_b128 v[168:171], v190 offset:20480
	ds_read_b128 v[172:175], v190 offset:21504
	ds_read_b128 v[176:179], v190 offset:22528
	ds_read_b128 v[180:183], v190 offset:23552
	v_lshl_add_u64 v[208:209], s[0:1], 0, v[164:165]
	v_lshl_add_u64 v[184:185], s[30:31], 0, v[162:163]
	s_add_i32 s30, s72, s5
	s_mov_b32 m0, s30
	s_nop 0
	global_load_lds_dwordx4 v[184:185], off
	v_lshl_add_u64 v[210:211], v[184:185], 0, s[12:13]
	s_add_i32 m0, s30, 0x2000
	s_nop 0
	global_load_lds_dwordx4 v[210:211], off
	s_add_i32 s0, s73, s5
	v_lshl_add_u64 v[250:251], v[184:185], 0, s[14:15]
	s_mov_b32 m0, s0
	s_nop 0
	global_load_lds_dwordx4 v[250:251], off
	v_lshl_add_u64 v[250:251], v[184:185], 0, s[16:17]
	s_add_i32 m0, s0, 0x2000
	s_nop 0
	global_load_lds_dwordx4 v[250:251], off
	s_mov_b32 m0, s6
	s_nop 0
	global_load_lds_dwordx4 v[208:209], off
	v_lshl_add_u64 v[210:211], v[208:209], 0, s[12:13]
	s_mov_b32 m0, s7
	s_nop 0
	global_load_lds_dwordx4 v[210:211], off
	s_cmp_lg_u32 s98, 0
	s_cbranch_scc1 .Lsk2_p13
	s_waitcnt vmcnt(8)
	s_branch .Lsk3_p13

.Lsk3_p13:
	s_waitcnt lgkmcnt(0)
	s_barrier
	v_mfma_f32_16x16x32_bf16 v[94:97], v[122:125], v[146:149], v[94:97]
	v_mfma_f32_16x16x32_bf16 v[90:93], v[138:141], v[146:149], v[90:93]
	v_mfma_f32_16x16x32_bf16 v[86:89], v[122:125], v[154:157], v[86:89]
	v_mfma_f32_16x16x32_bf16 v[82:85], v[138:141], v[154:157], v[82:85]
	v_mfma_f32_16x16x32_bf16 v[78:81], v[122:125], v[168:171], v[78:81]
	v_mfma_f32_16x16x32_bf16 v[74:77], v[138:141], v[168:171], v[74:77]
	v_mfma_f32_16x16x32_bf16 v[70:73], v[122:125], v[176:179], v[70:73]
	v_mfma_f32_16x16x32_bf16 v[66:69], v[138:141], v[176:179], v[66:69]
	v_mfma_f32_16x16x32_bf16 v[94:97], v[134:137], v[150:153], v[94:97]
	v_mfma_f32_16x16x32_bf16 v[90:93], v[142:145], v[150:153], v[90:93]
	v_mfma_f32_16x16x32_bf16 v[86:89], v[134:137], v[158:161], v[86:89]
	v_mfma_f32_16x16x32_bf16 v[82:85], v[142:145], v[158:161], v[82:85]
	v_mfma_f32_16x16x32_bf16 v[78:81], v[134:137], v[172:175], v[78:81]
	v_mfma_f32_16x16x32_bf16 v[74:77], v[142:145], v[172:175], v[74:77]
	v_mfma_f32_16x16x32_bf16 v[70:73], v[134:137], v[180:183], v[70:73]
	v_mfma_f32_16x16x32_bf16 v[66:69], v[142:145], v[180:183], v[66:69]
	v_mfma_f32_16x16x32_bf16 v[30:33], v[192:195], v[146:149], v[30:33]
	v_mfma_f32_16x16x32_bf16 v[26:29], v[200:203], v[146:149], v[26:29]
	v_mfma_f32_16x16x32_bf16 v[22:25], v[192:195], v[154:157], v[22:25]
	v_mfma_f32_16x16x32_bf16 v[18:21], v[200:203], v[154:157], v[18:21]
	v_mfma_f32_16x16x32_bf16 v[14:17], v[192:195], v[168:171], v[14:17]
	v_mfma_f32_16x16x32_bf16 v[10:13], v[200:203], v[168:171], v[10:13]
	v_mfma_f32_16x16x32_bf16 v[6:9], v[192:195], v[176:179], v[6:9]
	v_mfma_f32_16x16x32_bf16 v[2:5], v[200:203], v[176:179], v[2:5]
	v_mfma_f32_16x16x32_bf16 v[30:33], v[196:199], v[150:153], v[30:33]
	v_mfma_f32_16x16x32_bf16 v[26:29], v[204:207], v[150:153], v[26:29]
	v_mfma_f32_16x16x32_bf16 v[22:25], v[196:199], v[158:161], v[22:25]
	v_mfma_f32_16x16x32_bf16 v[18:21], v[204:207], v[158:161], v[18:21]
	v_mfma_f32_16x16x32_bf16 v[14:17], v[196:199], v[172:175], v[14:17]
	v_mfma_f32_16x16x32_bf16 v[10:13], v[204:207], v[172:175], v[10:13]
	v_mfma_f32_16x16x32_bf16 v[6:9], v[196:199], v[180:183], v[6:9]
	v_mfma_f32_16x16x32_bf16 v[2:5], v[204:207], v[180:183], v[2:5]
	s_add_i32 s0, 0, 0x18000
	v_add_u32_e32 v142, s0, v188
	s_barrier
	s_add_i32 s1, 0, 0x1c000
	v_add_u32_e32 v204, s1, v188
	ds_read_b128 v[122:125], v142
	ds_read_b128 v[134:137], v142 offset:1024
	ds_read_b128 v[138:141], v142 offset:2048
	ds_read_b128 v[142:145], v142 offset:3072
	ds_read_b128 v[192:195], v204
	ds_read_b128 v[196:199], v204 offset:1024
	ds_read_b128 v[200:203], v204 offset:2048
	ds_read_b128 v[204:207], v204 offset:3072
	s_mov_b32 m0, s24
	v_lshl_add_u64 v[252:253], v[208:209], 0, s[14:15]
	ds_read_b128 v[146:149], v190 offset:32768
	ds_read_b128 v[150:153], v190 offset:33792
	ds_read_b128 v[154:157], v190 offset:34816
	ds_read_b128 v[158:161], v190 offset:35840
	ds_read_b128 v[168:171], v190 offset:36864
	ds_read_b128 v[172:175], v190 offset:37888
	ds_read_b128 v[176:179], v190 offset:38912
	ds_read_b128 v[180:183], v190 offset:39936
	global_load_lds_dwordx4 v[252:253], off
	v_lshl_add_u64 v[252:253], v[208:209], 0, s[16:17]
	s_mov_b32 m0, s25
	s_nop 0
	global_load_lds_dwordx4 v[252:253], off
	s_waitcnt vmcnt(8)
	s_waitcnt lgkmcnt(0)
	s_barrier
	v_mfma_f32_16x16x32_bf16 v[130:133], v[122:125], v[146:149], v[130:133]
	v_mfma_f32_16x16x32_bf16 v[126:129], v[138:141], v[146:149], v[126:129]
	v_mfma_f32_16x16x32_bf16 v[118:121], v[122:125], v[154:157], v[118:121]
	v_mfma_f32_16x16x32_bf16 v[114:117], v[138:141], v[154:157], v[114:117]
	v_mfma_f32_16x16x32_bf16 v[110:113], v[122:125], v[168:171], v[110:113]
	v_mfma_f32_16x16x32_bf16 v[106:109], v[138:141], v[168:171], v[106:109]
	v_mfma_f32_16x16x32_bf16 v[102:105], v[122:125], v[176:179], v[102:105]
	v_mfma_f32_16x16x32_bf16 v[98:101], v[138:141], v[176:179], v[98:101]
	v_mfma_f32_16x16x32_bf16 v[130:133], v[134:137], v[150:153], v[130:133]
	v_mfma_f32_16x16x32_bf16 v[126:129], v[142:145], v[150:153], v[126:129]
	v_mfma_f32_16x16x32_bf16 v[118:121], v[134:137], v[158:161], v[118:121]
	v_mfma_f32_16x16x32_bf16 v[114:117], v[142:145], v[158:161], v[114:117]
	v_mfma_f32_16x16x32_bf16 v[110:113], v[134:137], v[172:175], v[110:113]
	v_mfma_f32_16x16x32_bf16 v[106:109], v[142:145], v[172:175], v[106:109]
	v_mfma_f32_16x16x32_bf16 v[102:105], v[134:137], v[180:183], v[102:105]
	v_mfma_f32_16x16x32_bf16 v[98:101], v[142:145], v[180:183], v[98:101]
	v_mfma_f32_16x16x32_bf16 v[62:65], v[192:195], v[146:149], v[62:65]
	v_mfma_f32_16x16x32_bf16 v[58:61], v[200:203], v[146:149], v[58:61]
	v_mfma_f32_16x16x32_bf16 v[54:57], v[192:195], v[154:157], v[54:57]
	v_mfma_f32_16x16x32_bf16 v[50:53], v[200:203], v[154:157], v[50:53]
	v_mfma_f32_16x16x32_bf16 v[46:49], v[192:195], v[168:171], v[46:49]
	v_mfma_f32_16x16x32_bf16 v[42:45], v[200:203], v[168:171], v[42:45]
	v_mfma_f32_16x16x32_bf16 v[38:41], v[192:195], v[176:179], v[38:41]
	v_mfma_f32_16x16x32_bf16 v[34:37], v[200:203], v[176:179], v[34:37]
	v_mfma_f32_16x16x32_bf16 v[62:65], v[196:199], v[150:153], v[62:65]
	v_mfma_f32_16x16x32_bf16 v[58:61], v[204:207], v[150:153], v[58:61]
	v_mfma_f32_16x16x32_bf16 v[54:57], v[196:199], v[158:161], v[54:57]
	v_mfma_f32_16x16x32_bf16 v[50:53], v[204:207], v[158:161], v[50:53]
	v_mfma_f32_16x16x32_bf16 v[46:49], v[196:199], v[172:175], v[46:49]
	v_mfma_f32_16x16x32_bf16 v[42:45], v[204:207], v[172:175], v[42:45]
	v_mfma_f32_16x16x32_bf16 v[38:41], v[196:199], v[180:183], v[38:41]
	v_mfma_f32_16x16x32_bf16 v[34:37], v[204:207], v[180:183], v[34:37]
	s_barrier
	ds_read_b128 v[146:149], v190 offset:49152
	ds_read_b128 v[150:153], v190 offset:50176
	ds_read_b128 v[154:157], v190 offset:51200
	ds_read_b128 v[158:161], v190 offset:52224
	ds_read_b128 v[168:171], v190 offset:53248
	ds_read_b128 v[172:175], v190 offset:54272
	ds_read_b128 v[176:179], v190 offset:55296
	ds_read_b128 v[180:183], v190 offset:56320
	s_add_i32 s0, s0, s5
	v_lshl_add_u64 v[210:211], v[184:185], 0, s[22:23]
	s_mov_b32 m0, s0
	s_nop 0
	global_load_lds_dwordx4 v[210:211], off
	v_lshl_add_u64 v[210:211], v[184:185], 0, s[34:35]
	s_add_i32 m0, s0, 0x2000
	s_nop 0
	global_load_lds_dwordx4 v[210:211], off
	s_add_i32 s0, s1, s5
	v_lshl_add_u64 v[250:251], v[184:185], 0, s[36:37]
	s_mov_b32 m0, s0
	s_nop 0
	global_load_lds_dwordx4 v[250:251], off
	v_lshl_add_u64 v[250:251], v[184:185], 0, s[38:39]
	s_add_i32 m0, s0, 0x2000
	s_nop 0
	global_load_lds_dwordx4 v[250:251], off
	s_mov_b32 m0, s66
	v_lshl_add_u64 v[210:211], v[208:209], 0, s[22:23]
	global_load_lds_dwordx4 v[210:211], off
	v_lshl_add_u64 v[208:209], v[208:209], 0, s[34:35]
	s_mov_b32 m0, s67
	s_nop 0
	global_load_lds_dwordx4 v[208:209], off
	s_waitcnt vmcnt(8)
	s_waitcnt lgkmcnt(0)
	s_barrier
	v_mfma_f32_16x16x32_bf16 v[94:97], v[122:125], v[146:149], v[94:97]
	v_mfma_f32_16x16x32_bf16 v[90:93], v[138:141], v[146:149], v[90:93]
	v_mfma_f32_16x16x32_bf16 v[86:89], v[122:125], v[154:157], v[86:89]
	v_mfma_f32_16x16x32_bf16 v[82:85], v[138:141], v[154:157], v[82:85]
	v_mfma_f32_16x16x32_bf16 v[78:81], v[122:125], v[168:171], v[78:81]
	v_mfma_f32_16x16x32_bf16 v[74:77], v[138:141], v[168:171], v[74:77]
	v_mfma_f32_16x16x32_bf16 v[70:73], v[122:125], v[176:179], v[70:73]
	v_mfma_f32_16x16x32_bf16 v[66:69], v[138:141], v[176:179], v[66:69]
	v_mfma_f32_16x16x32_bf16 v[94:97], v[134:137], v[150:153], v[94:97]
	v_mfma_f32_16x16x32_bf16 v[90:93], v[142:145], v[150:153], v[90:93]
	v_mfma_f32_16x16x32_bf16 v[86:89], v[134:137], v[158:161], v[86:89]
	v_mfma_f32_16x16x32_bf16 v[82:85], v[142:145], v[158:161], v[82:85]
	v_mfma_f32_16x16x32_bf16 v[78:81], v[134:137], v[172:175], v[78:81]
	v_mfma_f32_16x16x32_bf16 v[74:77], v[142:145], v[172:175], v[74:77]
	v_mfma_f32_16x16x32_bf16 v[70:73], v[134:137], v[180:183], v[70:73]
	v_mfma_f32_16x16x32_bf16 v[66:69], v[142:145], v[180:183], v[66:69]
	v_mfma_f32_16x16x32_bf16 v[30:33], v[192:195], v[146:149], v[30:33]
	v_mfma_f32_16x16x32_bf16 v[26:29], v[200:203], v[146:149], v[26:29]
	v_mfma_f32_16x16x32_bf16 v[22:25], v[192:195], v[154:157], v[22:25]
	v_mfma_f32_16x16x32_bf16 v[18:21], v[200:203], v[154:157], v[18:21]
	v_mfma_f32_16x16x32_bf16 v[14:17], v[192:195], v[168:171], v[14:17]
	v_mfma_f32_16x16x32_bf16 v[10:13], v[200:203], v[168:171], v[10:13]
	v_mfma_f32_16x16x32_bf16 v[6:9], v[192:195], v[176:179], v[6:9]
	v_mfma_f32_16x16x32_bf16 v[2:5], v[200:203], v[176:179], v[2:5]
	v_mfma_f32_16x16x32_bf16 v[30:33], v[196:199], v[150:153], v[30:33]
	v_mfma_f32_16x16x32_bf16 v[26:29], v[204:207], v[150:153], v[26:29]
	v_mfma_f32_16x16x32_bf16 v[22:25], v[196:199], v[158:161], v[22:25]
	v_mfma_f32_16x16x32_bf16 v[18:21], v[204:207], v[158:161], v[18:21]
	v_mfma_f32_16x16x32_bf16 v[14:17], v[196:199], v[172:175], v[14:17]
	v_mfma_f32_16x16x32_bf16 v[10:13], v[204:207], v[172:175], v[10:13]
	v_mfma_f32_16x16x32_bf16 v[6:9], v[196:199], v[180:183], v[6:9]
	v_mfma_f32_16x16x32_bf16 v[2:5], v[204:207], v[180:183], v[2:5]
	s_add_i32 s79, s79, 2
	s_add_u32 s62, s62, 0x100
	s_addc_u32 s63, s63, 0
	s_add_u32 s60, s60, 0x100
	s_addc_u32 s61, s61, 0
	s_cmp_gt_u32 s79, 13
	s_barrier
	s_cbranch_scc0 .LBB0_1631
	s_mov_b32 s98, 1
	s_and_b64 vcc, exec, s[40:41]
	s_cbranch_vccz .LBB0_1634
	s_barrier

.Lsk1_p14:
	s_waitcnt lgkmcnt(0)
	s_barrier
	v_mfma_f32_16x16x32_bf16 v[126:129], v[130:133], v[146:149], v[126:129]
	v_mfma_f32_16x16x32_bf16 v[122:125], v[138:141], v[146:149], v[122:125]
	v_mfma_f32_16x16x32_bf16 v[118:121], v[130:133], v[154:157], v[118:121]
	v_mfma_f32_16x16x32_bf16 v[114:117], v[138:141], v[154:157], v[114:117]
	v_mfma_f32_16x16x32_bf16 v[110:113], v[130:133], v[162:165], v[110:113]
	v_mfma_f32_16x16x32_bf16 v[106:109], v[138:141], v[162:165], v[106:109]
	v_mfma_f32_16x16x32_bf16 v[102:105], v[130:133], v[170:173], v[102:105]
	v_mfma_f32_16x16x32_bf16 v[98:101], v[138:141], v[170:173], v[98:101]
	v_mfma_f32_16x16x32_bf16 v[126:129], v[134:137], v[150:153], v[126:129]
	v_mfma_f32_16x16x32_bf16 v[122:125], v[142:145], v[150:153], v[122:125]
	v_mfma_f32_16x16x32_bf16 v[118:121], v[134:137], v[158:161], v[118:121]
	v_mfma_f32_16x16x32_bf16 v[114:117], v[142:145], v[158:161], v[114:117]
	v_mfma_f32_16x16x32_bf16 v[110:113], v[134:137], v[166:169], v[110:113]
	v_mfma_f32_16x16x32_bf16 v[106:109], v[142:145], v[166:169], v[106:109]
	v_mfma_f32_16x16x32_bf16 v[102:105], v[134:137], v[174:177], v[102:105]
	v_mfma_f32_16x16x32_bf16 v[98:101], v[142:145], v[174:177], v[98:101]
	v_mfma_f32_16x16x32_bf16 v[62:65], v[178:181], v[146:149], v[62:65]
	v_mfma_f32_16x16x32_bf16 v[58:61], v[186:189], v[146:149], v[58:61]
	v_mfma_f32_16x16x32_bf16 v[54:57], v[178:181], v[154:157], v[54:57]
	v_mfma_f32_16x16x32_bf16 v[50:53], v[186:189], v[154:157], v[50:53]
	v_mfma_f32_16x16x32_bf16 v[46:49], v[178:181], v[162:165], v[46:49]
	v_mfma_f32_16x16x32_bf16 v[42:45], v[186:189], v[162:165], v[42:45]
	v_mfma_f32_16x16x32_bf16 v[38:41], v[178:181], v[170:173], v[38:41]
	v_mfma_f32_16x16x32_bf16 v[34:37], v[186:189], v[170:173], v[34:37]
	v_mfma_f32_16x16x32_bf16 v[62:65], v[182:185], v[150:153], v[62:65]
	v_mfma_f32_16x16x32_bf16 v[58:61], v[190:193], v[150:153], v[58:61]
	v_mfma_f32_16x16x32_bf16 v[54:57], v[182:185], v[158:161], v[54:57]
	v_mfma_f32_16x16x32_bf16 v[50:53], v[190:193], v[158:161], v[50:53]
	v_mfma_f32_16x16x32_bf16 v[46:49], v[182:185], v[166:169], v[46:49]
	v_mfma_f32_16x16x32_bf16 v[42:45], v[190:193], v[166:169], v[42:45]
	v_mfma_f32_16x16x32_bf16 v[38:41], v[182:185], v[174:177], v[38:41]
	v_mfma_f32_16x16x32_bf16 v[34:37], v[190:193], v[174:177], v[34:37]
	s_barrier
	ds_read_b128 v[146:149], v214 offset:16384
	ds_read_b128 v[150:153], v214 offset:17408
	ds_read_b128 v[154:157], v214 offset:18432
	ds_read_b128 v[158:161], v214 offset:19456
	ds_read_b128 v[162:165], v214 offset:20480
	ds_read_b128 v[166:169], v214 offset:21504
	ds_read_b128 v[170:173], v214 offset:22528
	ds_read_b128 v[174:177], v214 offset:23552
	v_lshl_add_u64 v[202:203], s[0:1], 0, v[194:195]
	v_lshl_add_u64 v[200:201], s[30:31], 0, v[196:197]
	s_add_i32 s30, s73, s5
	s_mov_b32 m0, s30
	s_nop 0
	global_load_lds_dwordx4 v[200:201], off
	v_lshl_add_u64 v[204:205], v[200:201], 0, s[10:11]
	s_add_i32 m0, s30, 0x2000
	s_nop 0
	global_load_lds_dwordx4 v[204:205], off
	s_add_i32 s0, s74, s5
	v_lshl_add_u64 v[250:251], v[200:201], 0, s[16:17]
	s_mov_b32 m0, s0
	s_nop 0
	global_load_lds_dwordx4 v[250:251], off
	v_lshl_add_u64 v[250:251], v[200:201], 0, s[18:19]
	s_add_i32 m0, s0, 0x2000
	s_nop 0
	global_load_lds_dwordx4 v[250:251], off
	s_mov_b32 m0, s6
	s_nop 0
	global_load_lds_dwordx4 v[202:203], off
	v_lshl_add_u64 v[204:205], v[202:203], 0, s[10:11]
	s_mov_b32 m0, s7
	s_nop 0
	global_load_lds_dwordx4 v[204:205], off
	s_cmp_lg_u32 s98, 0
	s_cbranch_scc1 .Lsk2_p14
	s_waitcnt vmcnt(8)
	s_branch .Lsk3_p14

.Lsk3_p14:
	s_waitcnt lgkmcnt(0)
	s_barrier
	v_mfma_f32_16x16x32_bf16 v[94:97], v[130:133], v[146:149], v[94:97]
	v_mfma_f32_16x16x32_bf16 v[90:93], v[138:141], v[146:149], v[90:93]
	v_mfma_f32_16x16x32_bf16 v[86:89], v[130:133], v[154:157], v[86:89]
	v_mfma_f32_16x16x32_bf16 v[82:85], v[138:141], v[154:157], v[82:85]
	v_mfma_f32_16x16x32_bf16 v[78:81], v[130:133], v[162:165], v[78:81]
	v_mfma_f32_16x16x32_bf16 v[74:77], v[138:141], v[162:165], v[74:77]
	v_mfma_f32_16x16x32_bf16 v[70:73], v[130:133], v[170:173], v[70:73]
	v_mfma_f32_16x16x32_bf16 v[66:69], v[138:141], v[170:173], v[66:69]
	v_mfma_f32_16x16x32_bf16 v[94:97], v[134:137], v[150:153], v[94:97]
	v_mfma_f32_16x16x32_bf16 v[90:93], v[142:145], v[150:153], v[90:93]
	v_mfma_f32_16x16x32_bf16 v[86:89], v[134:137], v[158:161], v[86:89]
	v_mfma_f32_16x16x32_bf16 v[82:85], v[142:145], v[158:161], v[82:85]
	v_mfma_f32_16x16x32_bf16 v[78:81], v[134:137], v[166:169], v[78:81]
	v_mfma_f32_16x16x32_bf16 v[74:77], v[142:145], v[166:169], v[74:77]
	v_mfma_f32_16x16x32_bf16 v[70:73], v[134:137], v[174:177], v[70:73]
	v_mfma_f32_16x16x32_bf16 v[66:69], v[142:145], v[174:177], v[66:69]
	v_mfma_f32_16x16x32_bf16 v[30:33], v[178:181], v[146:149], v[30:33]
	v_mfma_f32_16x16x32_bf16 v[26:29], v[186:189], v[146:149], v[26:29]
	v_mfma_f32_16x16x32_bf16 v[22:25], v[178:181], v[154:157], v[22:25]
	v_mfma_f32_16x16x32_bf16 v[18:21], v[186:189], v[154:157], v[18:21]
	v_mfma_f32_16x16x32_bf16 v[14:17], v[178:181], v[162:165], v[14:17]
	v_mfma_f32_16x16x32_bf16 v[10:13], v[186:189], v[162:165], v[10:13]
	v_mfma_f32_16x16x32_bf16 v[6:9], v[178:181], v[170:173], v[6:9]
	v_mfma_f32_16x16x32_bf16 v[2:5], v[186:189], v[170:173], v[2:5]
	v_mfma_f32_16x16x32_bf16 v[30:33], v[182:185], v[150:153], v[30:33]
	v_mfma_f32_16x16x32_bf16 v[26:29], v[190:193], v[150:153], v[26:29]
	v_mfma_f32_16x16x32_bf16 v[22:25], v[182:185], v[158:161], v[22:25]
	v_mfma_f32_16x16x32_bf16 v[18:21], v[190:193], v[158:161], v[18:21]
	v_mfma_f32_16x16x32_bf16 v[14:17], v[182:185], v[166:169], v[14:17]
	v_mfma_f32_16x16x32_bf16 v[10:13], v[190:193], v[166:169], v[10:13]
	v_mfma_f32_16x16x32_bf16 v[6:9], v[182:185], v[174:177], v[6:9]
	v_mfma_f32_16x16x32_bf16 v[2:5], v[190:193], v[174:177], v[2:5]
	s_add_i32 s0, 0, 0x18000
	v_add_u32_e32 v142, s0, v212
	s_barrier
	s_add_i32 s1, 0, 0x1c000
	v_add_u32_e32 v190, s1, v212
	ds_read_b128 v[130:133], v142
	ds_read_b128 v[134:137], v142 offset:1024
	ds_read_b128 v[138:141], v142 offset:2048
	ds_read_b128 v[142:145], v142 offset:3072
	ds_read_b128 v[178:181], v190
	ds_read_b128 v[182:185], v190 offset:1024
	ds_read_b128 v[186:189], v190 offset:2048
	ds_read_b128 v[190:193], v190 offset:3072
	s_mov_b32 m0, s24
	v_lshl_add_u64 v[252:253], v[202:203], 0, s[16:17]
	ds_read_b128 v[146:149], v214 offset:32768
	ds_read_b128 v[150:153], v214 offset:33792
	ds_read_b128 v[154:157], v214 offset:34816
	ds_read_b128 v[158:161], v214 offset:35840
	ds_read_b128 v[162:165], v214 offset:36864
	ds_read_b128 v[166:169], v214 offset:37888
	ds_read_b128 v[170:173], v214 offset:38912
	ds_read_b128 v[174:177], v214 offset:39936
	global_load_lds_dwordx4 v[252:253], off
	v_lshl_add_u64 v[252:253], v[202:203], 0, s[18:19]
	s_mov_b32 m0, s25
	s_nop 0
	global_load_lds_dwordx4 v[252:253], off
	s_waitcnt vmcnt(8)
	s_waitcnt lgkmcnt(0)
	s_barrier
	v_mfma_f32_16x16x32_bf16 v[126:129], v[130:133], v[146:149], v[126:129]
	v_mfma_f32_16x16x32_bf16 v[122:125], v[138:141], v[146:149], v[122:125]
	v_mfma_f32_16x16x32_bf16 v[118:121], v[130:133], v[154:157], v[118:121]
	v_mfma_f32_16x16x32_bf16 v[114:117], v[138:141], v[154:157], v[114:117]
	v_mfma_f32_16x16x32_bf16 v[110:113], v[130:133], v[162:165], v[110:113]
	v_mfma_f32_16x16x32_bf16 v[106:109], v[138:141], v[162:165], v[106:109]
	v_mfma_f32_16x16x32_bf16 v[102:105], v[130:133], v[170:173], v[102:105]
	v_mfma_f32_16x16x32_bf16 v[98:101], v[138:141], v[170:173], v[98:101]
	v_mfma_f32_16x16x32_bf16 v[126:129], v[134:137], v[150:153], v[126:129]
	v_mfma_f32_16x16x32_bf16 v[122:125], v[142:145], v[150:153], v[122:125]
	v_mfma_f32_16x16x32_bf16 v[118:121], v[134:137], v[158:161], v[118:121]
	v_mfma_f32_16x16x32_bf16 v[114:117], v[142:145], v[158:161], v[114:117]
	v_mfma_f32_16x16x32_bf16 v[110:113], v[134:137], v[166:169], v[110:113]
	v_mfma_f32_16x16x32_bf16 v[106:109], v[142:145], v[166:169], v[106:109]
	v_mfma_f32_16x16x32_bf16 v[102:105], v[134:137], v[174:177], v[102:105]
	v_mfma_f32_16x16x32_bf16 v[98:101], v[142:145], v[174:177], v[98:101]
	v_mfma_f32_16x16x32_bf16 v[62:65], v[178:181], v[146:149], v[62:65]
	v_mfma_f32_16x16x32_bf16 v[58:61], v[186:189], v[146:149], v[58:61]
	v_mfma_f32_16x16x32_bf16 v[54:57], v[178:181], v[154:157], v[54:57]
	v_mfma_f32_16x16x32_bf16 v[50:53], v[186:189], v[154:157], v[50:53]
	v_mfma_f32_16x16x32_bf16 v[46:49], v[178:181], v[162:165], v[46:49]
	v_mfma_f32_16x16x32_bf16 v[42:45], v[186:189], v[162:165], v[42:45]
	v_mfma_f32_16x16x32_bf16 v[38:41], v[178:181], v[170:173], v[38:41]
	v_mfma_f32_16x16x32_bf16 v[34:37], v[186:189], v[170:173], v[34:37]
	v_mfma_f32_16x16x32_bf16 v[62:65], v[182:185], v[150:153], v[62:65]
	v_mfma_f32_16x16x32_bf16 v[58:61], v[190:193], v[150:153], v[58:61]
	v_mfma_f32_16x16x32_bf16 v[54:57], v[182:185], v[158:161], v[54:57]
	v_mfma_f32_16x16x32_bf16 v[50:53], v[190:193], v[158:161], v[50:53]
	v_mfma_f32_16x16x32_bf16 v[46:49], v[182:185], v[166:169], v[46:49]
	v_mfma_f32_16x16x32_bf16 v[42:45], v[190:193], v[166:169], v[42:45]
	v_mfma_f32_16x16x32_bf16 v[38:41], v[182:185], v[174:177], v[38:41]
	v_mfma_f32_16x16x32_bf16 v[34:37], v[190:193], v[174:177], v[34:37]
	s_barrier
	ds_read_b128 v[146:149], v214 offset:49152
	ds_read_b128 v[150:153], v214 offset:50176
	ds_read_b128 v[154:157], v214 offset:51200
	ds_read_b128 v[158:161], v214 offset:52224
	ds_read_b128 v[162:165], v214 offset:53248
	ds_read_b128 v[166:169], v214 offset:54272
	ds_read_b128 v[170:173], v214 offset:55296
	ds_read_b128 v[174:177], v214 offset:56320
	s_add_i32 s0, s0, s5
	v_lshl_add_u64 v[204:205], v[200:201], 0, s[38:39]
	s_mov_b32 m0, s0
	s_nop 0
	global_load_lds_dwordx4 v[204:205], off
	v_lshl_add_u64 v[204:205], v[200:201], 0, s[40:41]
	s_add_i32 m0, s0, 0x2000
	s_nop 0
	global_load_lds_dwordx4 v[204:205], off
	s_add_i32 s0, s1, s5
	v_lshl_add_u64 v[250:251], v[200:201], 0, s[42:43]
	s_mov_b32 m0, s0
	s_nop 0
	global_load_lds_dwordx4 v[250:251], off
	v_lshl_add_u64 v[250:251], v[200:201], 0, s[44:45]
	s_add_i32 m0, s0, 0x2000
	s_nop 0
	global_load_lds_dwordx4 v[250:251], off
	s_mov_b32 m0, s65
	v_lshl_add_u64 v[204:205], v[202:203], 0, s[38:39]
	global_load_lds_dwordx4 v[204:205], off
	v_lshl_add_u64 v[202:203], v[202:203], 0, s[40:41]
	s_mov_b32 m0, s66
	s_nop 0
	global_load_lds_dwordx4 v[202:203], off
	s_waitcnt vmcnt(8)
	s_waitcnt lgkmcnt(0)
	s_barrier
	v_mfma_f32_16x16x32_bf16 v[94:97], v[130:133], v[146:149], v[94:97]
	v_mfma_f32_16x16x32_bf16 v[90:93], v[138:141], v[146:149], v[90:93]
	v_mfma_f32_16x16x32_bf16 v[86:89], v[130:133], v[154:157], v[86:89]
	v_mfma_f32_16x16x32_bf16 v[82:85], v[138:141], v[154:157], v[82:85]
	v_mfma_f32_16x16x32_bf16 v[78:81], v[130:133], v[162:165], v[78:81]
	v_mfma_f32_16x16x32_bf16 v[74:77], v[138:141], v[162:165], v[74:77]
	v_mfma_f32_16x16x32_bf16 v[70:73], v[130:133], v[170:173], v[70:73]
	v_mfma_f32_16x16x32_bf16 v[66:69], v[138:141], v[170:173], v[66:69]
	v_mfma_f32_16x16x32_bf16 v[94:97], v[134:137], v[150:153], v[94:97]
	v_mfma_f32_16x16x32_bf16 v[90:93], v[142:145], v[150:153], v[90:93]
	v_mfma_f32_16x16x32_bf16 v[86:89], v[134:137], v[158:161], v[86:89]
	v_mfma_f32_16x16x32_bf16 v[82:85], v[142:145], v[158:161], v[82:85]
	v_mfma_f32_16x16x32_bf16 v[78:81], v[134:137], v[166:169], v[78:81]
	v_mfma_f32_16x16x32_bf16 v[74:77], v[142:145], v[166:169], v[74:77]
	v_mfma_f32_16x16x32_bf16 v[70:73], v[134:137], v[174:177], v[70:73]
	v_mfma_f32_16x16x32_bf16 v[66:69], v[142:145], v[174:177], v[66:69]
	v_mfma_f32_16x16x32_bf16 v[30:33], v[178:181], v[146:149], v[30:33]
	v_mfma_f32_16x16x32_bf16 v[26:29], v[186:189], v[146:149], v[26:29]
	v_mfma_f32_16x16x32_bf16 v[22:25], v[178:181], v[154:157], v[22:25]
	v_mfma_f32_16x16x32_bf16 v[18:21], v[186:189], v[154:157], v[18:21]
	v_mfma_f32_16x16x32_bf16 v[14:17], v[178:181], v[162:165], v[14:17]
	v_mfma_f32_16x16x32_bf16 v[10:13], v[186:189], v[162:165], v[10:13]
	v_mfma_f32_16x16x32_bf16 v[6:9], v[178:181], v[170:173], v[6:9]
	v_mfma_f32_16x16x32_bf16 v[2:5], v[186:189], v[170:173], v[2:5]
	v_mfma_f32_16x16x32_bf16 v[30:33], v[182:185], v[150:153], v[30:33]
	v_mfma_f32_16x16x32_bf16 v[26:29], v[190:193], v[150:153], v[26:29]
	v_mfma_f32_16x16x32_bf16 v[22:25], v[182:185], v[158:161], v[22:25]
	v_mfma_f32_16x16x32_bf16 v[18:21], v[190:193], v[158:161], v[18:21]
	v_mfma_f32_16x16x32_bf16 v[14:17], v[182:185], v[166:169], v[14:17]
	v_mfma_f32_16x16x32_bf16 v[10:13], v[190:193], v[166:169], v[10:13]
	v_mfma_f32_16x16x32_bf16 v[6:9], v[182:185], v[174:177], v[6:9]
	v_mfma_f32_16x16x32_bf16 v[2:5], v[190:193], v[174:177], v[2:5]
	s_add_i32 s86, s86, 2
	s_add_u32 s62, s62, 0x100
	s_addc_u32 s63, s63, 0
	s_add_u32 s60, s60, 0x100
	s_addc_u32 s61, s61, 0
	s_cmp_gt_u32 s86, 13
	s_barrier
	s_cbranch_scc0 .LBB0_1706
	s_mov_b32 s98, 1
	s_and_b64 vcc, exec, s[46:47]
	s_cbranch_vccz .LBB0_1709
	s_barrier
